# v3 + RN phase: the 32 split-K partial loads of context rows issued up front instead of 8 serial load-wait loops
# speedup vs baseline: 1.0089x; 1.0089x over previous
; __device__ __forceinline__ float bf_lo(unsigned w) { return __uint_as_float(w << 16); }
; __device__ __forceinline__ float bf_hi(unsigned w) { return __uint_as_float(w & 0xffff0000u); }
; __device__ __forceinline__ void load_bf4(const bf16_t* p, float* v) { const u32x2 w = *(const u32x2*)p; v[0] = bf_lo(w.x); v[1] = bf_hi(w.x); v[2] = bf_lo(w.y); v[3] = bf_hi(w.y); }
; __device__ __forceinline__ void phase_rn(const Params& p, int layer, int stage, const bf16_t* Y, int nrows, int npart) {
;     ...
;     for (int row = (blockIdx.x * 8 + wid) * 2; row < nrows; row += gridDim.x * 16) {
;         const int mr = modrow(row);
;         const float* xi = xin_row(p, row, from_input); float* xo = xout_row(p, row);
;         const bf16_t* y = Y + (size_t)row * DM;
;         const float* mg = MOD + ((size_t)layer * 17 + mr) * 6144 + gate_c * DM;
;         u32x2 yw[2][4]; f32x4 xx[2][4], gg[4], gt[4];
; #pragma unroll
;         for (int q = 0; q < 2; ++q)
; #pragma unroll
;             for (int i = 0; i < 4; ++i) { yw[q][i] = __builtin_nontemporal_load((const u32x2*)(y + q * DM + i * 256 + lane * 4)); xx[q][i] = __builtin_nontemporal_load((const f32x4*)(xi + q * DM + i * 256 + lane * 4)); }
; #pragma unroll
;         for (int i = 0; i < 4; ++i) { gg[i] = *(const f32x4*)(gA + i * 256 + lane * 4); gt[i] = *(const f32x4*)(mg + i * 256 + lane * 4); }
;         float yv[2][16]; float ss[2] = {0.f, 0.f};
; #pragma unroll
;         for (int q = 0; q < 2; ++q)
; #pragma unroll
;             for (int i = 0; i < 4; ++i) { yv[q][4 * i] = bf_lo(yw[q][i].x); yv[q][4 * i + 1] = bf_hi(yw[q][i].x); yv[q][4 * i + 2] = bf_lo(yw[q][i].y); yv[q][4 * i + 3] = bf_hi(yw[q][i].y); }
;         if (npart > 1 && row >= MLAT) {
;             const bf16_t* yp = (const bf16_t*)(p.ws + WS_SCR) + (size_t)(row - MLAT) * DM;
; #pragma unroll
;             for (int q = 0; q < 2; ++q)
; #pragma unroll
;                 for (int i = 0; i < 4; ++i) { float a4[4] = {0.f, 0.f, 0.f, 0.f};
;                     for (int k = 0; k < npart; ++k) { float t4[4]; load_bf4(yp + (size_t)k * MCTX * DM + q * DM + i * 256 + lane * 4, t4); a4[0] += t4[0]; a4[1] += t4[1]; a4[2] += t4[2]; a4[3] += t4[3]; }
;                     yv[q][4 * i] = a4[0]; yv[q][4 * i + 1] = a4[1]; yv[q][4 * i + 2] = a4[2]; yv[q][4 * i + 3] = a4[3]; }
.LBB0_315:
	v_min_i32_e32 v4, 0x8000, v64
	v_lshlrev_b64 v[2:3], 12, v[2:3]
	v_ashrrev_i32_e32 v65, 31, v64
	v_ashrrev_i32_e32 v141, 11, v4
	v_lshl_add_u64 v[0:1], v[0:1], 0, v[2:3]
	v_lshlrev_b64 v[94:95], 11, v[64:65]
	v_lshlrev_b32_e32 v98, 2, v66
	v_mov_b32_e32 v99, v97
	v_lshl_add_u64 v[2:3], v[68:69], 0, v[94:95]
	v_add_u32_e32 v4, s4, v141
	v_lshl_add_u64 v[0:1], v[0:1], 0, v[98:99]
	global_load_dwordx2 v[100:101], v[2:3], off offset:512 nt
	global_load_dwordx2 v[116:117], v[2:3], off offset:1024 nt
	global_load_dwordx2 v[102:103], v[2:3], off offset:1536 nt
	global_load_dwordx2 v[114:115], v[2:3], off nt
	global_load_dwordx4 v[12:15], v[0:1], off nt
	global_load_dwordx4 v[48:51], v[0:1], off offset:1024 nt
	global_load_dwordx2 v[118:119], v[2:3], off offset:2048 nt
	global_load_dwordx4 v[32:35], v[0:1], off offset:2048 nt
	global_load_dwordx4 v[28:31], v[0:1], off offset:3072 nt
	v_add_co_u32_e32 v0, vcc, s83, v0
	v_mul_hi_i32_i24_e32 v5, 0x6000, v4
	v_mul_i32_i24_e32 v4, 0x6000, v4
	v_addc_co_u32_e32 v1, vcc, 0, v1, vcc
	v_lshl_add_u64 v[4:5], v[72:73], 0, v[4:5]
	global_load_dwordx2 v[120:121], v[2:3], off offset:2560 nt
	global_load_dwordx4 v[16:19], v[0:1], off nt
	global_load_dwordx4 v[52:55], v[0:1], off offset:1024 nt
	global_load_dwordx2 v[126:127], v[2:3], off offset:3072 nt
	global_load_dwordx2 v[134:135], v[2:3], off offset:3584 nt
	global_load_dwordx4 v[36:39], v[0:1], off offset:2048 nt
	s_nop 0
	global_load_dwordx4 v[0:3], v[0:1], off offset:3072 nt
	s_nop 0
	global_load_dwordx4 v[20:23], v[70:71], off
	global_load_dwordx4 v[56:59], v[70:71], off offset:1024
	global_load_dwordx4 v[24:27], v[4:5], off
	global_load_dwordx4 v[60:63], v[4:5], off offset:1024
	global_load_dwordx4 v[40:43], v[70:71], off offset:2048
	global_load_dwordx4 v[8:11], v[70:71], off offset:3072
	global_load_dwordx4 v[44:47], v[4:5], off offset:2048
	s_nop 0
	global_load_dwordx4 v[4:7], v[4:5], off offset:3072
	v_cmp_lt_i32_e32 vcc, s37, v64
	v_add_u32_e32 v96, 0xffff8000, v64
	s_and_b64 s[6:7], s[26:27], vcc
	s_waitcnt vmcnt(0)
	v_lshlrev_b32_e32 v107, 16, v117
	v_and_b32_e32 v104, 0xffff0000, v100
	v_lshlrev_b32_e32 v105, 16, v100
	v_and_b32_e32 v112, 0xffff0000, v101
	v_lshlrev_b32_e32 v113, 16, v101
	v_and_b32_e32 v111, 0xffff0000, v102
	v_lshlrev_b32_e32 v110, 16, v102
	v_and_b32_e32 v109, 0xffff0000, v103
	v_lshlrev_b32_e32 v108, 16, v103
	v_lshlrev_b32_e32 v103, 16, v114
	v_lshlrev_b32_e32 v102, 16, v118
	v_and_b32_e32 v125, 0xffff0000, v114
	v_and_b32_e32 v124, 0xffff0000, v118
	v_lshlrev_b32_e32 v101, 16, v115
	v_lshlrev_b32_e32 v100, 16, v119
	v_and_b32_e32 v123, 0xffff0000, v115
	v_and_b32_e32 v122, 0xffff0000, v119
	v_and_b32_e32 v128, 0xffff0000, v120
	v_lshlrev_b32_e32 v129, 16, v120
	v_and_b32_e32 v114, 0xffff0000, v121
	v_lshlrev_b32_e32 v115, 16, v121
	v_lshlrev_b32_e32 v121, 16, v126
	v_lshlrev_b32_e32 v120, 16, v116
	v_and_b32_e32 v133, 0xffff0000, v116
	v_and_b32_e32 v132, 0xffff0000, v126
	v_lshlrev_b32_e32 v106, 16, v127
	v_and_b32_e32 v131, 0xffff0000, v117
	v_and_b32_e32 v130, 0xffff0000, v127
	v_and_b32_e32 v119, 0xffff0000, v134
	v_lshlrev_b32_e32 v118, 16, v134
	v_and_b32_e32 v117, 0xffff0000, v135
	v_lshlrev_b32_e32 v116, 16, v135
	s_and_saveexec_b64 s[14:15], s[6:7]
	s_cbranch_execz .LBB0_333
	v_lshlrev_b64 v[116:117], 11, v[96:97]
	v_lshl_add_u64 v[154:155], v[78:79], 0, v[116:117]
	global_load_dwordx2 v[216:217], v[154:155], off
	v_lshl_add_u64 v[156:157], v[154:155], 0, s[0:1]
	global_load_dwordx2 v[218:219], v[156:157], off
	v_lshl_add_u64 v[154:155], v[156:157], 0, s[0:1]
	global_load_dwordx2 v[220:221], v[154:155], off
	v_lshl_add_u64 v[156:157], v[154:155], 0, s[0:1]
	global_load_dwordx2 v[222:223], v[156:157], off
	v_lshl_add_u64 v[154:155], v[80:81], 0, v[116:117]
	global_load_dwordx2 v[224:225], v[154:155], off
	v_lshl_add_u64 v[156:157], v[154:155], 0, s[0:1]
	global_load_dwordx2 v[226:227], v[156:157], off
	v_lshl_add_u64 v[154:155], v[156:157], 0, s[0:1]
	global_load_dwordx2 v[228:229], v[154:155], off
	v_lshl_add_u64 v[156:157], v[154:155], 0, s[0:1]
	global_load_dwordx2 v[230:231], v[156:157], off
	v_lshl_add_u64 v[154:155], v[82:83], 0, v[116:117]
	global_load_dwordx2 v[232:233], v[154:155], off
	v_lshl_add_u64 v[156:157], v[154:155], 0, s[0:1]
	global_load_dwordx2 v[234:235], v[156:157], off
	v_lshl_add_u64 v[154:155], v[156:157], 0, s[0:1]
	global_load_dwordx2 v[236:237], v[154:155], off
	v_lshl_add_u64 v[156:157], v[154:155], 0, s[0:1]
	global_load_dwordx2 v[238:239], v[156:157], off
	v_lshl_add_u64 v[154:155], v[84:85], 0, v[116:117]
	global_load_dwordx2 v[240:241], v[154:155], off
	v_lshl_add_u64 v[156:157], v[154:155], 0, s[0:1]
	global_load_dwordx2 v[242:243], v[156:157], off
	v_lshl_add_u64 v[154:155], v[156:157], 0, s[0:1]
	global_load_dwordx2 v[244:245], v[154:155], off
	v_lshl_add_u64 v[156:157], v[154:155], 0, s[0:1]
	global_load_dwordx2 v[246:247], v[156:157], off
	v_lshl_add_u64 v[154:155], v[86:87], 0, v[116:117]
	global_load_dwordx2 v[248:249], v[154:155], off
	v_lshl_add_u64 v[156:157], v[154:155], 0, s[0:1]
	global_load_dwordx2 v[250:251], v[156:157], off
	v_lshl_add_u64 v[154:155], v[156:157], 0, s[0:1]
	global_load_dwordx2 v[160:161], v[154:155], off
	v_lshl_add_u64 v[156:157], v[154:155], 0, s[0:1]
	global_load_dwordx2 v[162:163], v[156:157], off
	v_lshl_add_u64 v[154:155], v[88:89], 0, v[116:117]
	global_load_dwordx2 v[164:165], v[154:155], off
	v_lshl_add_u64 v[156:157], v[154:155], 0, s[0:1]
	global_load_dwordx2 v[166:167], v[156:157], off
	v_lshl_add_u64 v[154:155], v[156:157], 0, s[0:1]
	global_load_dwordx2 v[168:169], v[154:155], off
	v_lshl_add_u64 v[156:157], v[154:155], 0, s[0:1]
	global_load_dwordx2 v[170:171], v[156:157], off
	v_lshl_add_u64 v[154:155], v[90:91], 0, v[116:117]
	global_load_dwordx2 v[172:173], v[154:155], off
	v_lshl_add_u64 v[156:157], v[154:155], 0, s[0:1]
	global_load_dwordx2 v[174:175], v[156:157], off
	v_lshl_add_u64 v[154:155], v[156:157], 0, s[0:1]
	global_load_dwordx2 v[176:177], v[154:155], off
	v_lshl_add_u64 v[156:157], v[154:155], 0, s[0:1]
	global_load_dwordx2 v[178:179], v[156:157], off
	v_lshl_add_u64 v[154:155], v[92:93], 0, v[116:117]
	global_load_dwordx2 v[180:181], v[154:155], off
	v_lshl_add_u64 v[156:157], v[154:155], 0, s[0:1]
	global_load_dwordx2 v[148:149], v[156:157], off
	v_lshl_add_u64 v[154:155], v[156:157], 0, s[0:1]
	global_load_dwordx2 v[150:151], v[154:155], off
	v_lshl_add_u64 v[156:157], v[154:155], 0, s[0:1]
	global_load_dwordx2 v[152:153], v[156:157], off
	v_mov_b32_e32 v100, 0
	v_lshl_add_u64 v[104:105], v[78:79], 0, v[116:117]
	s_mov_b32 s6, s92
	v_mov_b32_e32 v101, v100
	v_mov_b32_e32 v102, v100
	v_mov_b32_e32 v103, v100
; __device__ __forceinline__ void load_bf4(const bf16_t* p, float* v) { const u32x2 w = *(const u32x2*)p; v[0] = bf_lo(w.x); v[1] = bf_hi(w.x); v[2] = bf_lo(w.y); v[3] = bf_hi(w.y); }
; __device__ __forceinline__ void phase_rn(const Params& p, int layer, int stage, const bf16_t* Y, int nrows, int npart) {
;     ...
;             for (int q = 0; q < 2; ++q)
; #pragma unroll
;                 for (int i = 0; i < 4; ++i) { float a4[4] = {0.f, 0.f, 0.f, 0.f};
;                     for (int k = 0; k < npart; ++k) { float t4[4]; load_bf4(yp + (size_t)k * MCTX * DM + q * DM + i * 256 + lane * 4, t4); a4[0] += t4[0]; a4[1] += t4[1]; a4[2] += t4[2]; a4[3] += t4[3]; }
;                     yv[q][4 * i] = a4[0]; yv[q][4 * i + 1] = a4[1]; yv[q][4 * i + 2] = a4[2]; yv[q][4 * i + 3] = a4[3]; }
.LBB0_317:
	s_waitcnt vmcnt(28)
	v_and_b32_e32 v108, 0xffff0000, v216
	v_lshlrev_b32_e32 v109, 16, v216
	v_and_b32_e32 v106, 0xffff0000, v217
	v_lshlrev_b32_e32 v107, 16, v217
	v_pk_add_f32 v[102:103], v[102:103], v[108:109]
	v_pk_add_f32 v[100:101], v[100:101], v[106:107]
	v_and_b32_e32 v108, 0xffff0000, v218
	v_lshlrev_b32_e32 v109, 16, v218
	v_and_b32_e32 v106, 0xffff0000, v219
	v_lshlrev_b32_e32 v107, 16, v219
	v_pk_add_f32 v[102:103], v[102:103], v[108:109]
	v_pk_add_f32 v[100:101], v[100:101], v[106:107]
	v_and_b32_e32 v108, 0xffff0000, v220
	v_lshlrev_b32_e32 v109, 16, v220
	v_and_b32_e32 v106, 0xffff0000, v221
	v_lshlrev_b32_e32 v107, 16, v221
	v_pk_add_f32 v[102:103], v[102:103], v[108:109]
	v_pk_add_f32 v[100:101], v[100:101], v[106:107]
	v_and_b32_e32 v108, 0xffff0000, v222
	v_lshlrev_b32_e32 v109, 16, v222
	v_and_b32_e32 v106, 0xffff0000, v223
	v_lshlrev_b32_e32 v107, 16, v223
	v_pk_add_f32 v[102:103], v[102:103], v[108:109]
	v_pk_add_f32 v[100:101], v[100:101], v[106:107]
	v_mov_b32_e32 v112, 0
	v_lshl_add_u64 v[106:107], v[80:81], 0, v[116:117]
	s_mov_b32 s6, s92
	v_mov_b32_e32 v113, v112
	v_mov_b32_e32 v104, v112
	v_mov_b32_e32 v105, v112
.LBB0_319:
	s_waitcnt vmcnt(24)
	v_and_b32_e32 v110, 0xffff0000, v224
	v_lshlrev_b32_e32 v111, 16, v224
	v_and_b32_e32 v108, 0xffff0000, v225
	v_lshlrev_b32_e32 v109, 16, v225
	v_pk_add_f32 v[104:105], v[104:105], v[110:111]
	v_pk_add_f32 v[112:113], v[112:113], v[108:109]
	v_and_b32_e32 v110, 0xffff0000, v226
	v_lshlrev_b32_e32 v111, 16, v226
	v_and_b32_e32 v108, 0xffff0000, v227
	v_lshlrev_b32_e32 v109, 16, v227
	v_pk_add_f32 v[104:105], v[104:105], v[110:111]
	v_pk_add_f32 v[112:113], v[112:113], v[108:109]
	v_and_b32_e32 v110, 0xffff0000, v228
	v_lshlrev_b32_e32 v111, 16, v228
	v_and_b32_e32 v108, 0xffff0000, v229
	v_lshlrev_b32_e32 v109, 16, v229
	v_pk_add_f32 v[104:105], v[104:105], v[110:111]
	v_pk_add_f32 v[112:113], v[112:113], v[108:109]
	v_and_b32_e32 v110, 0xffff0000, v230
	v_lshlrev_b32_e32 v111, 16, v230
	v_and_b32_e32 v108, 0xffff0000, v231
	v_lshlrev_b32_e32 v109, 16, v231
	v_pk_add_f32 v[104:105], v[104:105], v[110:111]
	v_pk_add_f32 v[112:113], v[112:113], v[108:109]
	v_mov_b32_e32 v106, 0
	v_lshl_add_u64 v[108:109], v[82:83], 0, v[116:117]
	s_mov_b32 s6, s92
	v_mov_b32_e32 v107, v106
	v_mov_b32_e32 v126, v106
	v_mov_b32_e32 v127, v106
.LBB0_321:
	s_waitcnt vmcnt(20)
	v_and_b32_e32 v114, 0xffff0000, v232
	v_lshlrev_b32_e32 v115, 16, v232
	v_and_b32_e32 v110, 0xffff0000, v233
	v_lshlrev_b32_e32 v111, 16, v233
	v_pk_add_f32 v[126:127], v[126:127], v[114:115]
	v_pk_add_f32 v[106:107], v[106:107], v[110:111]
	v_and_b32_e32 v114, 0xffff0000, v234
	v_lshlrev_b32_e32 v115, 16, v234
	v_and_b32_e32 v110, 0xffff0000, v235
	v_lshlrev_b32_e32 v111, 16, v235
	v_pk_add_f32 v[126:127], v[126:127], v[114:115]
	v_pk_add_f32 v[106:107], v[106:107], v[110:111]
	v_and_b32_e32 v114, 0xffff0000, v236
	v_lshlrev_b32_e32 v115, 16, v236
	v_and_b32_e32 v110, 0xffff0000, v237
	v_lshlrev_b32_e32 v111, 16, v237
	v_pk_add_f32 v[126:127], v[126:127], v[114:115]
	v_pk_add_f32 v[106:107], v[106:107], v[110:111]
	v_and_b32_e32 v114, 0xffff0000, v238
	v_lshlrev_b32_e32 v115, 16, v238
	v_and_b32_e32 v110, 0xffff0000, v239
	v_lshlrev_b32_e32 v111, 16, v239
	v_pk_add_f32 v[126:127], v[126:127], v[114:115]
	v_pk_add_f32 v[106:107], v[106:107], v[110:111]
	v_mov_b32_e32 v108, 0
	v_lshl_add_u64 v[114:115], v[84:85], 0, v[116:117]
	s_mov_b32 s6, s92
	v_mov_b32_e32 v109, v108
	v_mov_b32_e32 v110, v108
	v_mov_b32_e32 v111, v108
.LBB0_323:
	s_waitcnt vmcnt(16)
	v_and_b32_e32 v121, 0xffff0000, v240
	v_lshlrev_b32_e32 v120, 16, v240
	v_and_b32_e32 v123, 0xffff0000, v241
	v_lshlrev_b32_e32 v122, 16, v241
	v_pk_add_f32 v[110:111], v[110:111], v[120:121]
	v_pk_add_f32 v[108:109], v[108:109], v[122:123]
	v_and_b32_e32 v121, 0xffff0000, v242
	v_lshlrev_b32_e32 v120, 16, v242
	v_and_b32_e32 v123, 0xffff0000, v243
	v_lshlrev_b32_e32 v122, 16, v243
	v_pk_add_f32 v[110:111], v[110:111], v[120:121]
	v_pk_add_f32 v[108:109], v[108:109], v[122:123]
	v_and_b32_e32 v121, 0xffff0000, v244
	v_lshlrev_b32_e32 v120, 16, v244
	v_and_b32_e32 v123, 0xffff0000, v245
	v_lshlrev_b32_e32 v122, 16, v245
	v_pk_add_f32 v[110:111], v[110:111], v[120:121]
	v_pk_add_f32 v[108:109], v[108:109], v[122:123]
	v_and_b32_e32 v121, 0xffff0000, v246
	v_lshlrev_b32_e32 v120, 16, v246
	v_and_b32_e32 v123, 0xffff0000, v247
	v_lshlrev_b32_e32 v122, 16, v247
	v_pk_add_f32 v[110:111], v[110:111], v[120:121]
	v_pk_add_f32 v[108:109], v[108:109], v[122:123]
	v_mov_b32_e32 v124, 0
	v_lshl_add_u64 v[114:115], v[86:87], 0, v[116:117]
	s_mov_b32 s6, s92
	v_mov_b32_e32 v125, v124
	v_mov_b32_e32 v134, v124
	v_mov_b32_e32 v135, v124
; __device__ __forceinline__ void load_bf4(const bf16_t* p, float* v) { const u32x2 w = *(const u32x2*)p; v[0] = bf_lo(w.x); v[1] = bf_hi(w.x); v[2] = bf_lo(w.y); v[3] = bf_hi(w.y); }
; __device__ __forceinline__ void phase_rn(const Params& p, int layer, int stage, const bf16_t* Y, int nrows, int npart) {
;     ...
;             for (int q = 0; q < 2; ++q)
; #pragma unroll
;                 for (int i = 0; i < 4; ++i) { float a4[4] = {0.f, 0.f, 0.f, 0.f};
;                     for (int k = 0; k < npart; ++k) { float t4[4]; load_bf4(yp + (size_t)k * MCTX * DM + q * DM + i * 256 + lane * 4, t4); a4[0] += t4[0]; a4[1] += t4[1]; a4[2] += t4[2]; a4[3] += t4[3]; }
;                     yv[q][4 * i] = a4[0]; yv[q][4 * i + 1] = a4[1]; yv[q][4 * i + 2] = a4[2]; yv[q][4 * i + 3] = a4[3]; }
.LBB0_325:
	s_waitcnt vmcnt(12)
	v_and_b32_e32 v120, 0xffff0000, v248
	v_lshlrev_b32_e32 v121, 16, v248
	v_and_b32_e32 v118, 0xffff0000, v249
	v_lshlrev_b32_e32 v119, 16, v249
	v_pk_add_f32 v[134:135], v[134:135], v[120:121]
	v_pk_add_f32 v[124:125], v[124:125], v[118:119]
	v_and_b32_e32 v120, 0xffff0000, v250
	v_lshlrev_b32_e32 v121, 16, v250
	v_and_b32_e32 v118, 0xffff0000, v251
	v_lshlrev_b32_e32 v119, 16, v251
	v_pk_add_f32 v[134:135], v[134:135], v[120:121]
	v_pk_add_f32 v[124:125], v[124:125], v[118:119]
	v_and_b32_e32 v120, 0xffff0000, v160
	v_lshlrev_b32_e32 v121, 16, v160
	v_and_b32_e32 v118, 0xffff0000, v161
	v_lshlrev_b32_e32 v119, 16, v161
	v_pk_add_f32 v[134:135], v[134:135], v[120:121]
	v_pk_add_f32 v[124:125], v[124:125], v[118:119]
	v_and_b32_e32 v120, 0xffff0000, v162
	v_lshlrev_b32_e32 v121, 16, v162
	v_and_b32_e32 v118, 0xffff0000, v163
	v_lshlrev_b32_e32 v119, 16, v163
	v_pk_add_f32 v[134:135], v[134:135], v[120:121]
	v_pk_add_f32 v[124:125], v[124:125], v[118:119]
	v_mov_b32_e32 v114, 0
	v_lshl_add_u64 v[118:119], v[88:89], 0, v[116:117]
	s_mov_b32 s6, s92
	v_mov_b32_e32 v115, v114
	v_mov_b32_e32 v128, v114
	v_mov_b32_e32 v129, v114
.LBB0_327:
	s_waitcnt vmcnt(8)
	v_and_b32_e32 v122, 0xffff0000, v164
	v_lshlrev_b32_e32 v123, 16, v164
	v_and_b32_e32 v120, 0xffff0000, v165
	v_lshlrev_b32_e32 v121, 16, v165
	v_pk_add_f32 v[128:129], v[128:129], v[122:123]
	v_pk_add_f32 v[114:115], v[114:115], v[120:121]
	v_and_b32_e32 v122, 0xffff0000, v166
	v_lshlrev_b32_e32 v123, 16, v166
	v_and_b32_e32 v120, 0xffff0000, v167
	v_lshlrev_b32_e32 v121, 16, v167
	v_pk_add_f32 v[128:129], v[128:129], v[122:123]
	v_pk_add_f32 v[114:115], v[114:115], v[120:121]
	v_and_b32_e32 v122, 0xffff0000, v168
	v_lshlrev_b32_e32 v123, 16, v168
	v_and_b32_e32 v120, 0xffff0000, v169
	v_lshlrev_b32_e32 v121, 16, v169
	v_pk_add_f32 v[128:129], v[128:129], v[122:123]
	v_pk_add_f32 v[114:115], v[114:115], v[120:121]
	v_and_b32_e32 v122, 0xffff0000, v170
	v_lshlrev_b32_e32 v123, 16, v170
	v_and_b32_e32 v120, 0xffff0000, v171
	v_lshlrev_b32_e32 v121, 16, v171
	v_pk_add_f32 v[128:129], v[128:129], v[122:123]
	v_pk_add_f32 v[114:115], v[114:115], v[120:121]
	v_mov_b32_e32 v122, 0
	v_lshl_add_u64 v[118:119], v[90:91], 0, v[116:117]
	s_mov_b32 s6, s92
	v_mov_b32_e32 v123, v122
	v_mov_b32_e32 v120, v122
	v_mov_b32_e32 v121, v122
.LBB0_329:
	s_waitcnt vmcnt(4)
	v_and_b32_e32 v132, 0xffff0000, v172
	v_lshlrev_b32_e32 v133, 16, v172
	v_and_b32_e32 v130, 0xffff0000, v173
	v_lshlrev_b32_e32 v131, 16, v173
	v_pk_add_f32 v[120:121], v[120:121], v[132:133]
	v_pk_add_f32 v[122:123], v[122:123], v[130:131]
	v_and_b32_e32 v132, 0xffff0000, v174
	v_lshlrev_b32_e32 v133, 16, v174
	v_and_b32_e32 v130, 0xffff0000, v175
	v_lshlrev_b32_e32 v131, 16, v175
	v_pk_add_f32 v[120:121], v[120:121], v[132:133]
	v_pk_add_f32 v[122:123], v[122:123], v[130:131]
	v_and_b32_e32 v132, 0xffff0000, v176
	v_lshlrev_b32_e32 v133, 16, v176
	v_and_b32_e32 v130, 0xffff0000, v177
	v_lshlrev_b32_e32 v131, 16, v177
	v_pk_add_f32 v[120:121], v[120:121], v[132:133]
	v_pk_add_f32 v[122:123], v[122:123], v[130:131]
	v_and_b32_e32 v132, 0xffff0000, v178
	v_lshlrev_b32_e32 v133, 16, v178
	v_and_b32_e32 v130, 0xffff0000, v179
	v_lshlrev_b32_e32 v131, 16, v179
	v_pk_add_f32 v[120:121], v[120:121], v[132:133]
	v_pk_add_f32 v[122:123], v[122:123], v[130:131]
	v_lshl_add_u64 v[130:131], v[92:93], 0, v[116:117]
	v_mov_b32_e32 v116, 0
	s_mov_b32 s6, s92
	v_mov_b32_e32 v117, v116
	v_mov_b32_e32 v118, v116
	v_mov_b32_e32 v119, v116
.LBB0_331:
	s_waitcnt vmcnt(0)
	v_and_b32_e32 v143, 0xffff0000, v180
	v_lshlrev_b32_e32 v142, 16, v180
	v_and_b32_e32 v145, 0xffff0000, v181
	v_lshlrev_b32_e32 v144, 16, v181
	v_pk_add_f32 v[118:119], v[118:119], v[142:143]
	v_pk_add_f32 v[116:117], v[116:117], v[144:145]
	v_and_b32_e32 v143, 0xffff0000, v148
	v_lshlrev_b32_e32 v142, 16, v148
	v_and_b32_e32 v145, 0xffff0000, v149
	v_lshlrev_b32_e32 v144, 16, v149
	v_pk_add_f32 v[118:119], v[118:119], v[142:143]
	v_pk_add_f32 v[116:117], v[116:117], v[144:145]
	v_and_b32_e32 v143, 0xffff0000, v150
	v_lshlrev_b32_e32 v142, 16, v150
	v_and_b32_e32 v145, 0xffff0000, v151
	v_lshlrev_b32_e32 v144, 16, v151
	v_pk_add_f32 v[118:119], v[118:119], v[142:143]
	v_pk_add_f32 v[116:117], v[116:117], v[144:145]
	v_and_b32_e32 v143, 0xffff0000, v152
	v_lshlrev_b32_e32 v142, 16, v152
	v_and_b32_e32 v145, 0xffff0000, v153
	v_lshlrev_b32_e32 v144, 16, v153
	v_pk_add_f32 v[118:119], v[118:119], v[142:143]
	v_pk_add_f32 v[116:117], v[116:117], v[144:145]
	v_mov_b32_e32 v130, v122
	v_mov_b32_e32 v131, v106
	v_mov_b32_e32 v106, v123
	v_mov_b32_e32 v132, v120
	v_mov_b32_e32 v133, v126
	v_mov_b32_e32 v122, v124
	v_mov_b32_e32 v123, v100
	v_mov_b32_e32 v100, v125
	v_mov_b32_e32 v124, v134
	v_mov_b32_e32 v125, v102
	v_mov_b32_e32 v102, v135
	v_mov_b32_e32 v120, v127
